# retB: device-scope write-through (sc1) on the 6 GATED stores ahead of the grid barrier, on top of the norm-phase write-through
# speedup vs baseline: 1.0111x; 1.0043x over previous
.LBB0_405:
	v_ashrrev_i32_e32 v92, 3, v73
	v_ashrrev_i32_e32 v93, 31, v92
	v_lshlrev_b64 v[2:3], 12, v[92:93]
	s_waitcnt vmcnt(24)
	v_and_b32_e32 v8, 0xc00, v94
	v_or_b32_e32 v9, v2, v72
	v_or_b32_e32 v2, v9, v8
	v_lshlrev_b64 v[0:1], 1, v[2:3]
	v_lshl_add_u64 v[4:5], s[44:45], 0, v[0:1]
	v_lshl_add_u64 v[0:1], s[48:49], 0, v[0:1]
	global_load_dwordx4 v[64:67], v[4:5], off nt
	global_load_dwordx4 v[68:71], v[0:1], off nt
	v_mov_b64_e32 v[0:1], s[40:41]
	v_mad_i64_i32 v[4:5], s[4:5], v92, s3, v[0:1]
	s_mov_b64 s[4:5], 0x18e04000
	s_nop 0
	v_lshl_add_u64 v[4:5], v[4:5], 0, s[4:5]
	v_lshlrev_b32_e32 v174, 1, v8
	v_lshl_add_u64 v[6:7], v[4:5], 0, v[174:175]
	v_lshlrev_b32_e32 v74, 1, v72
	v_mov_b32_e32 v75, v175
	v_lshl_add_u64 v[6:7], v[6:7], 0, v[74:75]
	v_or_b32_e32 v8, 0x200, v8
	global_load_dwordx4 v[60:63], v[6:7], off nt
	v_or_b32_e32 v2, v9, v8
	v_lshlrev_b64 v[2:3], 1, v[2:3]
	v_lshl_add_u64 v[6:7], s[44:45], 0, v[2:3]
	v_lshl_add_u64 v[2:3], s[48:49], 0, v[2:3]
	global_load_dwordx4 v[52:55], v[6:7], off nt
	global_load_dwordx4 v[56:59], v[2:3], off nt
	v_lshl_add_u64 v[2:3], v[4:5], 0, v[74:75]
	v_lshlrev_b32_e32 v4, 1, v8
	v_mov_b32_e32 v5, v175
	v_lshl_add_u64 v[2:3], v[2:3], 0, v[4:5]
	global_load_dwordx4 v[48:51], v[2:3], off nt
	v_add_u32_e32 v2, 2, v73
	v_ashrrev_i32_e32 v88, 3, v2
	v_ashrrev_i32_e32 v89, 31, v88
	v_add_u32_e32 v4, 0x400, v94
	v_lshlrev_b64 v[2:3], 12, v[88:89]
	v_and_b32_e32 v6, 0xc00, v4
	v_or_b32_e32 v2, v2, v6
	v_or_b32_e32 v2, v2, v72
	v_lshlrev_b64 v[2:3], 1, v[2:3]
	v_lshl_add_u64 v[4:5], s[44:45], 0, v[2:3]
	v_lshl_add_u64 v[2:3], s[48:49], 0, v[2:3]
	global_load_dwordx4 v[40:43], v[4:5], off nt
	global_load_dwordx4 v[44:47], v[2:3], off nt
	v_mad_i64_i32 v[2:3], s[4:5], v88, s3, v[0:1]
	v_lshlrev_b32_e32 v90, 1, v6
	v_mov_b32_e32 v91, v175
	v_lshl_add_u64 v[2:3], v[2:3], 0, v[90:91]
	v_lshl_add_u64 v[2:3], v[2:3], 0, v[74:75]
	v_add_co_u32_e32 v2, vcc, s22, v2
	v_add_u32_e32 v4, 0x600, v94
	s_nop 0
	v_addc_co_u32_e32 v3, vcc, 0, v3, vcc
	global_load_dwordx4 v[36:39], v[2:3], off nt
	v_add_u32_e32 v2, 3, v73
	v_ashrrev_i32_e32 v84, 3, v2
	v_ashrrev_i32_e32 v85, 31, v84
	v_lshlrev_b64 v[2:3], 12, v[84:85]
	v_and_b32_e32 v6, 0xe00, v4
	v_or_b32_e32 v2, v2, v6
	v_or_b32_e32 v2, v2, v72
	v_lshlrev_b64 v[2:3], 1, v[2:3]
	v_lshl_add_u64 v[4:5], s[44:45], 0, v[2:3]
	v_lshl_add_u64 v[2:3], s[48:49], 0, v[2:3]
	global_load_dwordx4 v[28:31], v[4:5], off nt
	global_load_dwordx4 v[32:35], v[2:3], off nt
	v_mad_i64_i32 v[2:3], s[4:5], v84, s3, v[0:1]
	v_lshlrev_b32_e32 v86, 1, v6
	v_mov_b32_e32 v87, v175
	v_lshl_add_u64 v[2:3], v[2:3], 0, v[86:87]
	v_lshl_add_u64 v[2:3], v[2:3], 0, v[74:75]
	v_add_co_u32_e32 v2, vcc, s22, v2
	v_add_u32_e32 v4, 0x800, v94
	s_nop 0
	v_addc_co_u32_e32 v3, vcc, 0, v3, vcc
	global_load_dwordx4 v[24:27], v[2:3], off nt
	v_add_u32_e32 v2, 4, v73
	v_ashrrev_i32_e32 v80, 3, v2
	v_ashrrev_i32_e32 v81, 31, v80
	v_lshlrev_b64 v[2:3], 12, v[80:81]
	v_and_b32_e32 v6, 0xc00, v4
	v_or_b32_e32 v2, v2, v6
	v_or_b32_e32 v2, v2, v72
	v_lshlrev_b64 v[2:3], 1, v[2:3]
	s_waitcnt vmcnt(10)
	v_lshlrev_b32_e32 v96, 16, v68
	v_lshlrev_b32_e32 v98, 16, v64
	v_lshlrev_b32_e32 v97, 16, v69
	v_lshlrev_b32_e32 v99, 16, v65
	v_lshl_add_u64 v[4:5], s[44:45], 0, v[2:3]
	v_lshl_add_u64 v[2:3], s[48:49], 0, v[2:3]
	v_and_b32_e32 v68, 0xffff0000, v68
	v_and_b32_e32 v64, 0xffff0000, v64
	v_and_b32_e32 v69, 0xffff0000, v69
	v_and_b32_e32 v65, 0xffff0000, v65
	v_pk_add_f32 v[96:97], v[98:99], v[96:97]
	v_lshlrev_b32_e32 v99, 16, v70
	v_lshlrev_b32_e32 v101, 16, v66
	v_lshlrev_b32_e32 v98, 16, v71
	v_lshlrev_b32_e32 v100, 16, v67
	global_load_dwordx4 v[16:19], v[4:5], off nt
	global_load_dwordx4 v[20:23], v[2:3], off nt
	v_mad_i64_i32 v[2:3], s[4:5], v80, s3, v[0:1]
	v_lshlrev_b32_e32 v82, 1, v6
	v_mov_b32_e32 v83, v175
	v_pk_add_f32 v[64:65], v[64:65], v[68:69]
	v_pk_mul_f32 v[68:69], v[96:97], v[96:97]
	v_and_b32_e32 v103, 0xffff0000, v70
	v_and_b32_e32 v105, 0xffff0000, v66
	v_and_b32_e32 v102, 0xffff0000, v71
	v_and_b32_e32 v104, 0xffff0000, v67
	v_pk_add_f32 v[66:67], v[100:101], v[98:99]
	v_lshl_add_u64 v[2:3], v[2:3], 0, v[82:83]
	v_pk_fma_f32 v[68:69], v[64:65], v[64:65], v[68:69]
	v_pk_add_f32 v[70:71], v[104:105], v[102:103]
	v_pk_mul_f32 v[98:99], v[66:67], v[66:67]
	v_lshl_add_u64 v[2:3], v[2:3], 0, v[74:75]
	v_pk_fma_f32 v[98:99], v[70:71], v[70:71], v[98:99]
	v_add_f32_e32 v68, v68, v69
	v_add_co_u32_e32 v2, vcc, s22, v2
	v_add_f32_e32 v68, v99, v68
	s_nop 0
	v_addc_co_u32_e32 v3, vcc, 0, v3, vcc
	v_add_f32_e32 v68, v98, v68
	global_load_dwordx4 v[12:15], v[2:3], off nt
	v_add_u32_e32 v2, 5, v73
	v_add_f32_dpp v68, v68, v68 row_ror:8 row_mask:0xf bank_mask:0xf bound_ctrl:1
	v_ashrrev_i32_e32 v78, 3, v2
	v_ashrrev_i32_e32 v79, 31, v78
	v_add_f32_dpp v68, v68, v68 row_ror:4 row_mask:0xf bank_mask:0xf bound_ctrl:1
	v_add_u32_e32 v4, 0xa00, v94
	v_lshlrev_b64 v[2:3], 12, v[78:79]
	v_add_f32_dpp v68, v68, v68 row_ror:2 row_mask:0xf bank_mask:0xf bound_ctrl:1
	v_and_b32_e32 v76, 0xe00, v4
	v_or_b32_e32 v2, v2, v76
	v_add_f32_dpp v68, v68, v68 row_ror:1 row_mask:0xf bank_mask:0xf bound_ctrl:1
	v_mad_i64_i32 v[0:1], s[4:5], v78, s3, v[0:1]
	v_lshlrev_b32_e32 v76, 1, v76
	v_mov_b32_e32 v77, v175
	v_readlane_b32 s1, v68, 16
	v_readlane_b32 s2, v68, 48
	v_lshl_add_u64 v[0:1], v[0:1], 0, v[76:77]
	v_readlane_b32 s4, v68, 0
	v_readlane_b32 s5, v68, 32
	v_mov_b32_e32 v68, s1
	v_mov_b32_e32 v69, s2
	v_lshl_add_u64 v[0:1], v[0:1], 0, v[74:75]
	v_pk_add_f32 v[68:69], s[4:5], v[68:69]
	v_add_co_u32_e32 v0, vcc, s22, v0
	v_add_f32_e32 v68, v68, v69
	s_nop 0
	v_addc_co_u32_e32 v1, vcc, 0, v1, vcc
	v_fmamk_f32 v68, v68, 0x3b000000, v173
	v_cmp_gt_f32_e32 vcc, s19, v68
	v_mul_f32_e32 v69, 0x4f800000, v68
	v_or_b32_e32 v2, v2, v72
	v_cndmask_b32_e32 v68, v68, v69, vcc
	v_sqrt_f32_e32 v69, v68
	v_lshlrev_b64 v[2:3], 1, v[2:3]
	v_lshl_add_u64 v[4:5], s[44:45], 0, v[2:3]
	v_lshl_add_u64 v[2:3], s[48:49], 0, v[2:3]
	v_add_u32_e32 v95, -1, v69
	v_fma_f32 v98, -v95, v69, v68
	v_cmp_ge_f32_e64 s[38:39], 0, v98
	v_add_u32_e32 v98, 1, v69
	global_load_dwordx4 v[4:7], v[4:5], off nt
	v_cndmask_b32_e64 v95, v69, v95, s[38:39]
	v_fma_f32 v69, -v98, v69, v68
	v_cmp_lt_f32_e64 s[38:39], 0, v69
	global_load_dwordx4 v[8:11], v[2:3], off nt
	s_nop 0
	v_cndmask_b32_e64 v69, v95, v98, s[38:39]
	v_mul_f32_e32 v95, 0x37800000, v69
	v_cndmask_b32_e32 v69, v69, v95, vcc
	v_cmp_class_f32_e32 vcc, v68, v244
	global_load_dwordx4 v[0:3], v[0:1], off nt
	s_nop 0
	v_cndmask_b32_e32 v68, v69, v68, vcc
	v_div_scale_f32 v69, s[4:5], v68, v68, 1.0
	v_rcp_f32_e32 v95, v69
	s_nop 0
	v_fma_f32 v98, -v69, v95, 1.0
	v_fmac_f32_e32 v95, v98, v95
	v_div_scale_f32 v98, vcc, 1.0, v68, 1.0
	v_mul_f32_e32 v99, v98, v95
	v_fma_f32 v100, -v69, v99, v98
	v_fmac_f32_e32 v99, v100, v95
	v_fma_f32 v69, -v69, v99, v98
	v_div_fmas_f32 v69, v69, v95, v99
	v_div_fixup_f32 v68, v69, v68, 1.0
	s_waitcnt vmcnt(15)
	v_lshlrev_b32_e32 v69, 16, v60
	v_mul_f32_e32 v95, 0xbfb8aa3b, v69
	v_exp_f32_e32 v95, v95
	v_and_b32_e32 v60, 0xffff0000, v60
	v_add_f32_e32 v95, 1.0, v95
	v_div_scale_f32 v98, s[4:5], v95, v95, v69
	v_rcp_f32_e32 v99, v98
	s_nop 0
	v_fma_f32 v100, -v98, v99, 1.0
	v_fmac_f32_e32 v99, v100, v99
	v_div_scale_f32 v100, vcc, v69, v95, v69
	v_mul_f32_e32 v101, v100, v99
	v_fma_f32 v102, -v98, v101, v100
	v_fmac_f32_e32 v101, v102, v99
	v_fma_f32 v98, -v98, v101, v100
	v_div_fmas_f32 v98, v98, v99, v101
	v_div_fixup_f32 v69, v98, v95, v69
	v_mul_f32_e32 v95, 0xbfb8aa3b, v60
	v_exp_f32_e32 v95, v95
	v_mul_f32_e32 v69, v96, v69
	v_mul_f32_e32 v69, v69, v68
	v_add_f32_e32 v95, 1.0, v95
	v_div_scale_f32 v96, s[4:5], v95, v95, v60
	v_rcp_f32_e32 v98, v96
	s_nop 0
	v_fma_f32 v99, -v96, v98, 1.0
	v_fmac_f32_e32 v98, v99, v98
	v_div_scale_f32 v99, vcc, v60, v95, v60
	v_mul_f32_e32 v100, v99, v98
	v_fma_f32 v101, -v96, v100, v99
	v_fmac_f32_e32 v100, v101, v98
	v_fma_f32 v96, -v96, v100, v99
	v_div_fmas_f32 v96, v96, v98, v100
	v_div_fixup_f32 v60, v96, v95, v60
	v_mul_f32_e32 v60, v64, v60
	v_mul_f32_e32 v60, v60, v68
	v_lshlrev_b32_e32 v64, 16, v61
	v_cvt_pk_bf16_f32 v60, v69, v60
	v_mul_f32_e32 v69, 0xbfb8aa3b, v64
	v_exp_f32_e32 v69, v69
	v_and_b32_e32 v61, 0xffff0000, v61
	v_add_f32_e32 v69, 1.0, v69
	v_div_scale_f32 v95, s[4:5], v69, v69, v64
	v_rcp_f32_e32 v96, v95
	s_nop 0
	v_fma_f32 v98, -v95, v96, 1.0
	v_fmac_f32_e32 v96, v98, v96
	v_div_scale_f32 v98, vcc, v64, v69, v64
	v_mul_f32_e32 v99, v98, v96
	v_fma_f32 v100, -v95, v99, v98
	v_fmac_f32_e32 v99, v100, v96
	v_fma_f32 v95, -v95, v99, v98
	v_div_fmas_f32 v95, v95, v96, v99
	v_div_fixup_f32 v64, v95, v69, v64
	v_mul_f32_e32 v69, 0xbfb8aa3b, v61
	v_exp_f32_e32 v69, v69
	v_mul_f32_e32 v64, v97, v64
	v_mul_f32_e32 v64, v64, v68
	v_add_f32_e32 v69, 1.0, v69
	v_div_scale_f32 v95, s[4:5], v69, v69, v61
	v_rcp_f32_e32 v96, v95
	s_nop 0
	v_fma_f32 v97, -v95, v96, 1.0
	v_fmac_f32_e32 v96, v97, v96
	v_div_scale_f32 v97, vcc, v61, v69, v61
	v_mul_f32_e32 v98, v97, v96
	v_fma_f32 v99, -v95, v98, v97
	v_fmac_f32_e32 v98, v99, v96
	v_fma_f32 v95, -v95, v98, v97
	v_div_fmas_f32 v95, v95, v96, v98
	v_div_fixup_f32 v61, v95, v69, v61
	v_mul_f32_e32 v61, v65, v61
	v_mul_f32_e32 v61, v61, v68
	v_cvt_pk_bf16_f32 v61, v64, v61
	v_lshlrev_b32_e32 v64, 16, v62
	v_mul_f32_e32 v65, 0xbfb8aa3b, v64
	v_exp_f32_e32 v65, v65
	v_and_b32_e32 v62, 0xffff0000, v62
	v_add_f32_e32 v65, 1.0, v65
	v_div_scale_f32 v69, s[4:5], v65, v65, v64
	v_rcp_f32_e32 v95, v69
	s_nop 0
	v_fma_f32 v96, -v69, v95, 1.0
	v_fmac_f32_e32 v95, v96, v95
	v_div_scale_f32 v96, vcc, v64, v65, v64
	v_mul_f32_e32 v97, v96, v95
	v_fma_f32 v98, -v69, v97, v96
	v_fmac_f32_e32 v97, v98, v95
	v_fma_f32 v69, -v69, v97, v96
	v_div_fmas_f32 v69, v69, v95, v97
	v_div_fixup_f32 v64, v69, v65, v64
	v_mul_f32_e32 v65, 0xbfb8aa3b, v62
	v_exp_f32_e32 v65, v65
	v_mul_f32_e32 v64, v67, v64
	v_mul_f32_e32 v64, v64, v68
	v_add_f32_e32 v65, 1.0, v65
	v_div_scale_f32 v67, s[4:5], v65, v65, v62
	v_rcp_f32_e32 v69, v67
	s_nop 0
	v_fma_f32 v95, -v67, v69, 1.0
	v_fmac_f32_e32 v69, v95, v69
	v_div_scale_f32 v95, vcc, v62, v65, v62
	v_mul_f32_e32 v96, v95, v69
	v_fma_f32 v97, -v67, v96, v95
	v_fmac_f32_e32 v96, v97, v69
	v_fma_f32 v67, -v67, v96, v95
	v_div_fmas_f32 v67, v67, v69, v96
	v_div_fixup_f32 v62, v67, v65, v62
	v_mul_f32_e32 v62, v71, v62
	v_mul_f32_e32 v62, v62, v68
	v_cvt_pk_bf16_f32 v62, v64, v62
	v_lshlrev_b32_e32 v64, 16, v63
	v_mul_f32_e32 v65, 0xbfb8aa3b, v64
	v_exp_f32_e32 v65, v65
	v_and_b32_e32 v63, 0xffff0000, v63
	v_add_f32_e32 v65, 1.0, v65
	v_div_scale_f32 v67, s[4:5], v65, v65, v64
	v_rcp_f32_e32 v69, v67
	s_nop 0
	v_fma_f32 v71, -v67, v69, 1.0
	v_fmac_f32_e32 v69, v71, v69
	v_div_scale_f32 v71, vcc, v64, v65, v64
	v_mul_f32_e32 v95, v71, v69
	v_fma_f32 v96, -v67, v95, v71
	v_fmac_f32_e32 v95, v96, v69
	v_fma_f32 v67, -v67, v95, v71
	v_div_fmas_f32 v67, v67, v69, v95
	v_div_fixup_f32 v64, v67, v65, v64
	v_mul_f32_e32 v65, 0xbfb8aa3b, v63
	v_exp_f32_e32 v65, v65
	v_mul_f32_e32 v64, v66, v64
	v_mul_f32_e32 v64, v64, v68
	v_add_f32_e32 v65, 1.0, v65
	v_div_scale_f32 v66, s[4:5], v65, v65, v63
	v_rcp_f32_e32 v67, v66
	s_nop 0
	v_fma_f32 v69, -v66, v67, 1.0
	v_fmac_f32_e32 v67, v69, v67
	v_div_scale_f32 v69, vcc, v63, v65, v63
	v_mul_f32_e32 v71, v69, v67
	v_fma_f32 v95, -v66, v71, v69
	v_fmac_f32_e32 v71, v95, v67
	v_fma_f32 v66, -v66, v71, v69
	v_div_fmas_f32 v66, v66, v67, v71
	v_div_fixup_f32 v63, v66, v65, v63
	v_mul_f32_e32 v63, v70, v63
	v_mul_f32_e32 v63, v63, v68
	v_cvt_pk_bf16_f32 v63, v64, v63
	v_lshlrev_b64 v[64:65], 13, v[92:93]
	v_lshl_add_u64 v[64:65], s[46:47], 0, v[64:65]
	v_lshl_add_u64 v[64:65], v[64:65], 0, v[174:175]
	v_lshl_add_u64 v[64:65], v[64:65], 0, v[74:75]
	global_store_dwordx4 v[64:65], v[60:63], off sc1
	s_waitcnt vmcnt(15)
	v_lshlrev_b32_e32 v67, 16, v54
	v_lshlrev_b32_e32 v66, 16, v55
	s_waitcnt vmcnt(14)
	v_lshlrev_b32_e32 v60, 16, v56
	v_lshlrev_b32_e32 v62, 16, v52
	v_lshlrev_b32_e32 v61, 16, v57
	v_lshlrev_b32_e32 v63, 16, v53
	v_and_b32_e32 v56, 0xffff0000, v56
	v_and_b32_e32 v52, 0xffff0000, v52
	v_and_b32_e32 v57, 0xffff0000, v57
	v_and_b32_e32 v53, 0xffff0000, v53
	v_pk_add_f32 v[60:61], v[62:63], v[60:61]
	v_lshlrev_b32_e32 v63, 16, v58
	v_lshlrev_b32_e32 v62, 16, v59
	v_pk_add_f32 v[52:53], v[52:53], v[56:57]
	v_pk_mul_f32 v[56:57], v[60:61], v[60:61]
	v_and_b32_e32 v69, 0xffff0000, v58
	v_and_b32_e32 v71, 0xffff0000, v54
	v_and_b32_e32 v68, 0xffff0000, v59
	v_and_b32_e32 v70, 0xffff0000, v55
	v_pk_add_f32 v[54:55], v[66:67], v[62:63]
	v_pk_fma_f32 v[56:57], v[52:53], v[52:53], v[56:57]
	v_pk_add_f32 v[58:59], v[70:71], v[68:69]
	v_pk_mul_f32 v[62:63], v[54:55], v[54:55]
	v_add_f32_e32 v56, v56, v57
	v_pk_fma_f32 v[62:63], v[58:59], v[58:59], v[62:63]
	s_nop 0
	v_add_f32_e32 v56, v63, v56
	v_add_f32_e32 v56, v62, v56
	s_nop 1
	v_add_f32_dpp v56, v56, v56 row_ror:8 row_mask:0xf bank_mask:0xf bound_ctrl:1
	s_nop 1
	v_add_f32_dpp v56, v56, v56 row_ror:4 row_mask:0xf bank_mask:0xf bound_ctrl:1
	s_nop 1
	v_add_f32_dpp v56, v56, v56 row_ror:2 row_mask:0xf bank_mask:0xf bound_ctrl:1
	s_nop 1
	v_add_f32_dpp v56, v56, v56 row_ror:1 row_mask:0xf bank_mask:0xf bound_ctrl:1
	s_nop 0
	v_readlane_b32 s1, v56, 16
	v_readlane_b32 s2, v56, 48
	v_readlane_b32 s4, v56, 0
	v_readlane_b32 s5, v56, 32
	v_mov_b32_e32 v56, s1
	v_mov_b32_e32 v57, s2
	v_pk_add_f32 v[56:57], s[4:5], v[56:57]
	s_nop 0
	v_add_f32_e32 v56, v56, v57
	v_fmamk_f32 v56, v56, 0x3b000000, v173
	v_cmp_gt_f32_e32 vcc, s19, v56
	v_mul_f32_e32 v57, 0x4f800000, v56
	s_nop 0
	v_cndmask_b32_e32 v56, v56, v57, vcc
	v_sqrt_f32_e32 v57, v56
	s_nop 0
	v_add_u32_e32 v62, -1, v57
	v_fma_f32 v63, -v62, v57, v56
	v_cmp_ge_f32_e64 s[38:39], 0, v63
	v_add_u32_e32 v63, 1, v57
	s_nop 0
	v_cndmask_b32_e64 v62, v57, v62, s[38:39]
	v_fma_f32 v57, -v63, v57, v56
	v_cmp_lt_f32_e64 s[38:39], 0, v57
	s_nop 1
	v_cndmask_b32_e64 v57, v62, v63, s[38:39]
	v_mul_f32_e32 v62, 0x37800000, v57
	v_cndmask_b32_e32 v57, v57, v62, vcc
	v_cmp_class_f32_e32 vcc, v56, v244
	s_nop 1
	v_cndmask_b32_e32 v56, v57, v56, vcc
	v_div_scale_f32 v57, s[4:5], v56, v56, 1.0
	v_rcp_f32_e32 v62, v57
	s_nop 0
	v_fma_f32 v63, -v57, v62, 1.0
	v_fmac_f32_e32 v62, v63, v62
	v_div_scale_f32 v63, vcc, 1.0, v56, 1.0
	v_mul_f32_e32 v66, v63, v62
	v_fma_f32 v67, -v57, v66, v63
	v_fmac_f32_e32 v66, v67, v62
	v_fma_f32 v57, -v57, v66, v63
	v_div_fmas_f32 v57, v57, v62, v66
	v_div_fixup_f32 v56, v57, v56, 1.0
	s_waitcnt vmcnt(13)
	v_lshlrev_b32_e32 v57, 16, v48
	v_mul_f32_e32 v62, 0xbfb8aa3b, v57
	v_exp_f32_e32 v62, v62
	v_and_b32_e32 v48, 0xffff0000, v48
	v_add_f32_e32 v62, 1.0, v62
	v_div_scale_f32 v63, s[4:5], v62, v62, v57
	v_rcp_f32_e32 v66, v63
	s_nop 0
	v_fma_f32 v67, -v63, v66, 1.0
	v_fmac_f32_e32 v66, v67, v66
	v_div_scale_f32 v67, vcc, v57, v62, v57
	v_mul_f32_e32 v68, v67, v66
	v_fma_f32 v69, -v63, v68, v67
	v_fmac_f32_e32 v68, v69, v66
	v_fma_f32 v63, -v63, v68, v67
	v_div_fmas_f32 v63, v63, v66, v68
	v_div_fixup_f32 v57, v63, v62, v57
	v_mul_f32_e32 v57, v60, v57
	v_mul_f32_e32 v60, 0xbfb8aa3b, v48
	v_exp_f32_e32 v60, v60
	v_mul_f32_e32 v57, v57, v56
	v_add_f32_e32 v60, 1.0, v60
	v_div_scale_f32 v62, s[4:5], v60, v60, v48
	v_rcp_f32_e32 v63, v62
	s_nop 0
	v_fma_f32 v66, -v62, v63, 1.0
	v_fmac_f32_e32 v63, v66, v63
	v_div_scale_f32 v66, vcc, v48, v60, v48
	v_mul_f32_e32 v67, v66, v63
	v_fma_f32 v68, -v62, v67, v66
	v_fmac_f32_e32 v67, v68, v63
	v_fma_f32 v62, -v62, v67, v66
	v_div_fmas_f32 v62, v62, v63, v67
	v_div_fixup_f32 v48, v62, v60, v48
	v_mul_f32_e32 v48, v52, v48
	v_mul_f32_e32 v48, v48, v56
	v_lshlrev_b32_e32 v52, 16, v49
	v_cvt_pk_bf16_f32 v48, v57, v48
	v_mul_f32_e32 v57, 0xbfb8aa3b, v52
	v_exp_f32_e32 v57, v57
	v_and_b32_e32 v49, 0xffff0000, v49
	v_add_f32_e32 v57, 1.0, v57
	v_div_scale_f32 v60, s[4:5], v57, v57, v52
	v_rcp_f32_e32 v62, v60
	s_nop 0
	v_fma_f32 v63, -v60, v62, 1.0
	v_fmac_f32_e32 v62, v63, v62
	v_div_scale_f32 v63, vcc, v52, v57, v52
	v_mul_f32_e32 v66, v63, v62
	v_fma_f32 v67, -v60, v66, v63
	v_fmac_f32_e32 v66, v67, v62
	v_fma_f32 v60, -v60, v66, v63
	v_div_fmas_f32 v60, v60, v62, v66
	v_div_fixup_f32 v52, v60, v57, v52
	v_mul_f32_e32 v57, 0xbfb8aa3b, v49
	v_exp_f32_e32 v57, v57
	v_mul_f32_e32 v52, v61, v52
	v_mul_f32_e32 v52, v52, v56
	v_add_f32_e32 v57, 1.0, v57
	v_div_scale_f32 v60, s[4:5], v57, v57, v49
	v_rcp_f32_e32 v61, v60
	s_nop 0
	v_fma_f32 v62, -v60, v61, 1.0
	v_fmac_f32_e32 v61, v62, v61
	v_div_scale_f32 v62, vcc, v49, v57, v49
	v_mul_f32_e32 v63, v62, v61
	v_fma_f32 v66, -v60, v63, v62
	v_fmac_f32_e32 v63, v66, v61
	v_fma_f32 v60, -v60, v63, v62
	v_div_fmas_f32 v60, v60, v61, v63
	v_div_fixup_f32 v49, v60, v57, v49
	v_mul_f32_e32 v49, v53, v49
	v_mul_f32_e32 v49, v49, v56
	v_cvt_pk_bf16_f32 v49, v52, v49
	v_lshlrev_b32_e32 v52, 16, v50
	v_mul_f32_e32 v53, 0xbfb8aa3b, v52
	v_exp_f32_e32 v53, v53
	v_and_b32_e32 v50, 0xffff0000, v50
	v_add_f32_e32 v53, 1.0, v53
	v_div_scale_f32 v57, s[4:5], v53, v53, v52
	v_rcp_f32_e32 v60, v57
	s_nop 0
	v_fma_f32 v61, -v57, v60, 1.0
	v_fmac_f32_e32 v60, v61, v60
	v_div_scale_f32 v61, vcc, v52, v53, v52
	v_mul_f32_e32 v62, v61, v60
	v_fma_f32 v63, -v57, v62, v61
	v_fmac_f32_e32 v62, v63, v60
	v_fma_f32 v57, -v57, v62, v61
	v_div_fmas_f32 v57, v57, v60, v62
	v_div_fixup_f32 v52, v57, v53, v52
	v_mul_f32_e32 v53, 0xbfb8aa3b, v50
	v_exp_f32_e32 v53, v53
	v_mul_f32_e32 v52, v55, v52
	v_mul_f32_e32 v52, v52, v56
	v_add_f32_e32 v53, 1.0, v53
	v_div_scale_f32 v55, s[4:5], v53, v53, v50
	v_rcp_f32_e32 v57, v55
	s_nop 0
	v_fma_f32 v60, -v55, v57, 1.0
	v_fmac_f32_e32 v57, v60, v57
	v_div_scale_f32 v60, vcc, v50, v53, v50
	v_mul_f32_e32 v61, v60, v57
	v_fma_f32 v62, -v55, v61, v60
	v_fmac_f32_e32 v61, v62, v57
	v_fma_f32 v55, -v55, v61, v60
	v_div_fmas_f32 v55, v55, v57, v61
	v_div_fixup_f32 v50, v55, v53, v50
	v_mul_f32_e32 v50, v59, v50
	v_mul_f32_e32 v50, v50, v56
	v_cvt_pk_bf16_f32 v50, v52, v50
	v_lshlrev_b32_e32 v52, 16, v51
	v_mul_f32_e32 v53, 0xbfb8aa3b, v52
	v_exp_f32_e32 v53, v53
	v_and_b32_e32 v51, 0xffff0000, v51
	v_add_f32_e32 v53, 1.0, v53
	v_div_scale_f32 v55, s[4:5], v53, v53, v52
	v_rcp_f32_e32 v57, v55
	s_nop 0
	v_fma_f32 v59, -v55, v57, 1.0
	v_fmac_f32_e32 v57, v59, v57
	v_div_scale_f32 v59, vcc, v52, v53, v52
	v_mul_f32_e32 v60, v59, v57
	v_fma_f32 v61, -v55, v60, v59
	v_fmac_f32_e32 v60, v61, v57
	v_fma_f32 v55, -v55, v60, v59
	v_div_fmas_f32 v55, v55, v57, v60
	v_div_fixup_f32 v52, v55, v53, v52
	v_mul_f32_e32 v53, 0xbfb8aa3b, v51
	v_exp_f32_e32 v53, v53
	v_mul_f32_e32 v52, v54, v52
	v_mul_f32_e32 v52, v52, v56
	v_add_f32_e32 v53, 1.0, v53
	v_div_scale_f32 v54, s[4:5], v53, v53, v51
	v_rcp_f32_e32 v55, v54
	s_nop 0
	v_fma_f32 v57, -v54, v55, 1.0
	v_fmac_f32_e32 v55, v57, v55
	v_div_scale_f32 v57, vcc, v51, v53, v51
	v_mul_f32_e32 v59, v57, v55
	v_fma_f32 v60, -v54, v59, v57
	v_fmac_f32_e32 v59, v60, v55
	v_fma_f32 v54, -v54, v59, v57
	v_div_fmas_f32 v54, v54, v55, v59
	v_div_fixup_f32 v51, v54, v53, v51
	v_mul_f32_e32 v51, v58, v51
	v_mul_f32_e32 v51, v51, v56
	v_cvt_pk_bf16_f32 v51, v52, v51
	global_store_dwordx4 v[64:65], v[48:51], off offset:1024 sc1
	s_waitcnt vmcnt(13)
	v_lshlrev_b32_e32 v53, 16, v42
	v_lshlrev_b32_e32 v52, 16, v43
	s_waitcnt vmcnt(12)
	v_lshlrev_b32_e32 v48, 16, v44
	v_lshlrev_b32_e32 v50, 16, v40
	v_lshlrev_b32_e32 v49, 16, v45
	v_lshlrev_b32_e32 v51, 16, v41
	v_and_b32_e32 v44, 0xffff0000, v44
	v_and_b32_e32 v40, 0xffff0000, v40
	v_and_b32_e32 v45, 0xffff0000, v45
	v_and_b32_e32 v41, 0xffff0000, v41
	v_pk_add_f32 v[48:49], v[50:51], v[48:49]
	v_lshlrev_b32_e32 v51, 16, v46
	v_lshlrev_b32_e32 v50, 16, v47
	v_pk_add_f32 v[40:41], v[40:41], v[44:45]
	v_pk_mul_f32 v[44:45], v[48:49], v[48:49]
	v_and_b32_e32 v55, 0xffff0000, v46
	v_and_b32_e32 v57, 0xffff0000, v42
	v_and_b32_e32 v54, 0xffff0000, v47
	v_and_b32_e32 v56, 0xffff0000, v43
	v_pk_add_f32 v[42:43], v[52:53], v[50:51]
	v_pk_fma_f32 v[44:45], v[40:41], v[40:41], v[44:45]
	v_pk_add_f32 v[46:47], v[56:57], v[54:55]
	v_pk_mul_f32 v[50:51], v[42:43], v[42:43]
	v_add_f32_e32 v44, v44, v45
	v_pk_fma_f32 v[50:51], v[46:47], v[46:47], v[50:51]
	s_nop 0
	v_add_f32_e32 v44, v51, v44
	v_add_f32_e32 v44, v50, v44
	s_nop 1
	v_add_f32_dpp v44, v44, v44 row_ror:8 row_mask:0xf bank_mask:0xf bound_ctrl:1
	s_nop 1
	v_add_f32_dpp v44, v44, v44 row_ror:4 row_mask:0xf bank_mask:0xf bound_ctrl:1
	s_nop 1
	v_add_f32_dpp v44, v44, v44 row_ror:2 row_mask:0xf bank_mask:0xf bound_ctrl:1
	s_nop 1
	v_add_f32_dpp v44, v44, v44 row_ror:1 row_mask:0xf bank_mask:0xf bound_ctrl:1
	s_nop 0
	v_readlane_b32 s1, v44, 16
	v_readlane_b32 s2, v44, 48
	v_readlane_b32 s4, v44, 0
	v_readlane_b32 s5, v44, 32
	v_mov_b32_e32 v44, s1
	v_mov_b32_e32 v45, s2
	v_pk_add_f32 v[44:45], s[4:5], v[44:45]
	s_nop 0
	v_add_f32_e32 v44, v44, v45
	v_fmamk_f32 v44, v44, 0x3b000000, v173
	v_cmp_gt_f32_e32 vcc, s19, v44
	v_mul_f32_e32 v45, 0x4f800000, v44
	s_nop 0
	v_cndmask_b32_e32 v44, v44, v45, vcc
	v_sqrt_f32_e32 v45, v44
	s_nop 0
	v_add_u32_e32 v50, -1, v45
	v_fma_f32 v51, -v50, v45, v44
	v_cmp_ge_f32_e64 s[38:39], 0, v51
	v_add_u32_e32 v51, 1, v45
	s_nop 0
	v_cndmask_b32_e64 v50, v45, v50, s[38:39]
	v_fma_f32 v45, -v51, v45, v44
	v_cmp_lt_f32_e64 s[38:39], 0, v45
	s_nop 1
	v_cndmask_b32_e64 v45, v50, v51, s[38:39]
	v_mul_f32_e32 v50, 0x37800000, v45
	v_cndmask_b32_e32 v45, v45, v50, vcc
	v_cmp_class_f32_e32 vcc, v44, v244
	s_nop 1
	v_cndmask_b32_e32 v44, v45, v44, vcc
	v_div_scale_f32 v45, s[4:5], v44, v44, 1.0
	v_rcp_f32_e32 v50, v45
	s_nop 0
	v_fma_f32 v51, -v45, v50, 1.0
	v_fmac_f32_e32 v50, v51, v50
	v_div_scale_f32 v51, vcc, 1.0, v44, 1.0
	v_mul_f32_e32 v52, v51, v50
	v_fma_f32 v53, -v45, v52, v51
	v_fmac_f32_e32 v52, v53, v50
	v_fma_f32 v45, -v45, v52, v51
	v_div_fmas_f32 v45, v45, v50, v52
	v_div_fixup_f32 v44, v45, v44, 1.0
	s_waitcnt vmcnt(11)
	v_lshlrev_b32_e32 v45, 16, v36
	v_mul_f32_e32 v50, 0xbfb8aa3b, v45
	v_exp_f32_e32 v50, v50
	v_and_b32_e32 v36, 0xffff0000, v36
	v_add_f32_e32 v50, 1.0, v50
	v_div_scale_f32 v51, s[4:5], v50, v50, v45
	v_rcp_f32_e32 v52, v51
	s_nop 0
	v_fma_f32 v53, -v51, v52, 1.0
	v_fmac_f32_e32 v52, v53, v52
	v_div_scale_f32 v53, vcc, v45, v50, v45
	v_mul_f32_e32 v54, v53, v52
	v_fma_f32 v55, -v51, v54, v53
	v_fmac_f32_e32 v54, v55, v52
	v_fma_f32 v51, -v51, v54, v53
	v_div_fmas_f32 v51, v51, v52, v54
	v_div_fixup_f32 v45, v51, v50, v45
	v_mul_f32_e32 v45, v48, v45
	v_mul_f32_e32 v48, 0xbfb8aa3b, v36
	v_exp_f32_e32 v48, v48
	v_mul_f32_e32 v45, v45, v44
	v_add_f32_e32 v48, 1.0, v48
	v_div_scale_f32 v50, s[4:5], v48, v48, v36
	v_rcp_f32_e32 v51, v50
	s_nop 0
	v_fma_f32 v52, -v50, v51, 1.0
	v_fmac_f32_e32 v51, v52, v51
	v_div_scale_f32 v52, vcc, v36, v48, v36
	v_mul_f32_e32 v53, v52, v51
	v_fma_f32 v54, -v50, v53, v52
	v_fmac_f32_e32 v53, v54, v51
	v_fma_f32 v50, -v50, v53, v52
	v_div_fmas_f32 v50, v50, v51, v53
	v_div_fixup_f32 v36, v50, v48, v36
	v_mul_f32_e32 v36, v40, v36
	v_mul_f32_e32 v36, v36, v44
	v_lshlrev_b32_e32 v40, 16, v37
	v_cvt_pk_bf16_f32 v36, v45, v36
	v_mul_f32_e32 v45, 0xbfb8aa3b, v40
	v_exp_f32_e32 v45, v45
	v_and_b32_e32 v37, 0xffff0000, v37
	v_add_f32_e32 v45, 1.0, v45
	v_div_scale_f32 v48, s[4:5], v45, v45, v40
	v_rcp_f32_e32 v50, v48
	s_nop 0
	v_fma_f32 v51, -v48, v50, 1.0
	v_fmac_f32_e32 v50, v51, v50
	v_div_scale_f32 v51, vcc, v40, v45, v40
	v_mul_f32_e32 v52, v51, v50
	v_fma_f32 v53, -v48, v52, v51
	v_fmac_f32_e32 v52, v53, v50
	v_fma_f32 v48, -v48, v52, v51
	v_div_fmas_f32 v48, v48, v50, v52
	v_div_fixup_f32 v40, v48, v45, v40
	v_mul_f32_e32 v45, 0xbfb8aa3b, v37
	v_exp_f32_e32 v45, v45
	v_mul_f32_e32 v40, v49, v40
	v_mul_f32_e32 v40, v40, v44
	v_add_f32_e32 v45, 1.0, v45
	v_div_scale_f32 v48, s[4:5], v45, v45, v37
	v_rcp_f32_e32 v49, v48
	s_nop 0
	v_fma_f32 v50, -v48, v49, 1.0
	v_fmac_f32_e32 v49, v50, v49
	v_div_scale_f32 v50, vcc, v37, v45, v37
	v_mul_f32_e32 v51, v50, v49
	v_fma_f32 v52, -v48, v51, v50
	v_fmac_f32_e32 v51, v52, v49
	v_fma_f32 v48, -v48, v51, v50
	v_div_fmas_f32 v48, v48, v49, v51
	v_div_fixup_f32 v37, v48, v45, v37
	v_mul_f32_e32 v37, v41, v37
	v_mul_f32_e32 v37, v37, v44
	v_cvt_pk_bf16_f32 v37, v40, v37
	v_lshlrev_b32_e32 v40, 16, v38
	v_mul_f32_e32 v41, 0xbfb8aa3b, v40
	v_exp_f32_e32 v41, v41
	v_and_b32_e32 v38, 0xffff0000, v38
	v_add_f32_e32 v41, 1.0, v41
	v_div_scale_f32 v45, s[4:5], v41, v41, v40
	v_rcp_f32_e32 v48, v45
	s_nop 0
	v_fma_f32 v49, -v45, v48, 1.0
	v_fmac_f32_e32 v48, v49, v48
	v_div_scale_f32 v49, vcc, v40, v41, v40
	v_mul_f32_e32 v50, v49, v48
	v_fma_f32 v51, -v45, v50, v49
	v_fmac_f32_e32 v50, v51, v48
	v_fma_f32 v45, -v45, v50, v49
	v_div_fmas_f32 v45, v45, v48, v50
	v_div_fixup_f32 v40, v45, v41, v40
	v_mul_f32_e32 v41, 0xbfb8aa3b, v38
	v_exp_f32_e32 v41, v41
	v_mul_f32_e32 v40, v43, v40
	v_mul_f32_e32 v40, v40, v44
	v_add_f32_e32 v41, 1.0, v41
	v_div_scale_f32 v43, s[4:5], v41, v41, v38
	v_rcp_f32_e32 v45, v43
	s_nop 0
	v_fma_f32 v48, -v43, v45, 1.0
	v_fmac_f32_e32 v45, v48, v45
	v_div_scale_f32 v48, vcc, v38, v41, v38
	v_mul_f32_e32 v49, v48, v45
	v_fma_f32 v50, -v43, v49, v48
	v_fmac_f32_e32 v49, v50, v45
	v_fma_f32 v43, -v43, v49, v48
	v_div_fmas_f32 v43, v43, v45, v49
	v_div_fixup_f32 v38, v43, v41, v38
	v_mul_f32_e32 v38, v47, v38
	v_mul_f32_e32 v38, v38, v44
	v_cvt_pk_bf16_f32 v38, v40, v38
	v_lshlrev_b32_e32 v40, 16, v39
	v_mul_f32_e32 v41, 0xbfb8aa3b, v40
	v_exp_f32_e32 v41, v41
	v_and_b32_e32 v39, 0xffff0000, v39
	v_add_f32_e32 v41, 1.0, v41
	v_div_scale_f32 v43, s[4:5], v41, v41, v40
	v_rcp_f32_e32 v45, v43
	s_nop 0
	v_fma_f32 v47, -v43, v45, 1.0
	v_fmac_f32_e32 v45, v47, v45
	v_div_scale_f32 v47, vcc, v40, v41, v40
	v_mul_f32_e32 v48, v47, v45
	v_fma_f32 v49, -v43, v48, v47
	v_fmac_f32_e32 v48, v49, v45
	v_fma_f32 v43, -v43, v48, v47
	v_div_fmas_f32 v43, v43, v45, v48
	v_div_fixup_f32 v40, v43, v41, v40
	v_mul_f32_e32 v41, 0xbfb8aa3b, v39
	v_exp_f32_e32 v41, v41
	v_mul_f32_e32 v40, v42, v40
	v_mul_f32_e32 v40, v40, v44
	v_add_f32_e32 v41, 1.0, v41
	v_div_scale_f32 v42, s[4:5], v41, v41, v39
	v_rcp_f32_e32 v43, v42
	s_nop 0
	v_fma_f32 v45, -v42, v43, 1.0
	v_fmac_f32_e32 v43, v45, v43
	v_div_scale_f32 v45, vcc, v39, v41, v39
	v_mul_f32_e32 v47, v45, v43
	v_fma_f32 v48, -v42, v47, v45
	v_fmac_f32_e32 v47, v48, v43
	v_fma_f32 v42, -v42, v47, v45
	v_div_fmas_f32 v42, v42, v43, v47
	v_div_fixup_f32 v39, v42, v41, v39
	v_mul_f32_e32 v39, v46, v39
	v_mul_f32_e32 v39, v39, v44
	v_cvt_pk_bf16_f32 v39, v40, v39
	v_lshlrev_b64 v[40:41], 13, v[88:89]
	v_lshl_add_u64 v[40:41], s[46:47], 0, v[40:41]
	v_lshl_add_u64 v[40:41], v[40:41], 0, v[90:91]
	v_lshl_add_u64 v[40:41], v[40:41], 0, v[74:75]
	global_store_dwordx4 v[40:41], v[36:39], off sc1
	s_waitcnt vmcnt(11)
	v_lshlrev_b32_e32 v41, 16, v30
	v_lshlrev_b32_e32 v40, 16, v31
	s_waitcnt vmcnt(10)
	v_lshlrev_b32_e32 v36, 16, v32
	v_lshlrev_b32_e32 v38, 16, v28
	v_lshlrev_b32_e32 v37, 16, v33
	v_lshlrev_b32_e32 v39, 16, v29
	v_and_b32_e32 v32, 0xffff0000, v32
	v_and_b32_e32 v28, 0xffff0000, v28
	v_and_b32_e32 v33, 0xffff0000, v33
	v_and_b32_e32 v29, 0xffff0000, v29
	v_pk_add_f32 v[36:37], v[38:39], v[36:37]
	v_lshlrev_b32_e32 v39, 16, v34
	v_lshlrev_b32_e32 v38, 16, v35
	v_pk_add_f32 v[28:29], v[28:29], v[32:33]
	v_pk_mul_f32 v[32:33], v[36:37], v[36:37]
	v_and_b32_e32 v43, 0xffff0000, v34
	v_and_b32_e32 v45, 0xffff0000, v30
	v_and_b32_e32 v42, 0xffff0000, v35
	v_and_b32_e32 v44, 0xffff0000, v31
	v_pk_add_f32 v[30:31], v[40:41], v[38:39]
	v_pk_fma_f32 v[32:33], v[28:29], v[28:29], v[32:33]
	v_pk_add_f32 v[34:35], v[44:45], v[42:43]
	v_pk_mul_f32 v[38:39], v[30:31], v[30:31]
	v_add_f32_e32 v32, v32, v33
	v_pk_fma_f32 v[38:39], v[34:35], v[34:35], v[38:39]
	s_nop 0
	v_add_f32_e32 v32, v39, v32
	v_add_f32_e32 v32, v38, v32
	s_nop 1
	v_add_f32_dpp v32, v32, v32 row_ror:8 row_mask:0xf bank_mask:0xf bound_ctrl:1
	s_nop 1
	v_add_f32_dpp v32, v32, v32 row_ror:4 row_mask:0xf bank_mask:0xf bound_ctrl:1
	s_nop 1
	v_add_f32_dpp v32, v32, v32 row_ror:2 row_mask:0xf bank_mask:0xf bound_ctrl:1
	s_nop 1
	v_add_f32_dpp v32, v32, v32 row_ror:1 row_mask:0xf bank_mask:0xf bound_ctrl:1
	s_nop 0
	v_readlane_b32 s1, v32, 16
	v_readlane_b32 s2, v32, 48
	v_readlane_b32 s4, v32, 0
	v_readlane_b32 s5, v32, 32
	v_mov_b32_e32 v32, s1
	v_mov_b32_e32 v33, s2
	v_pk_add_f32 v[32:33], s[4:5], v[32:33]
	s_nop 0
	v_add_f32_e32 v32, v32, v33
	v_fmamk_f32 v32, v32, 0x3b000000, v173
	v_cmp_gt_f32_e32 vcc, s19, v32
	v_mul_f32_e32 v33, 0x4f800000, v32
	s_nop 0
	v_cndmask_b32_e32 v32, v32, v33, vcc
	v_sqrt_f32_e32 v33, v32
	s_nop 0
	v_add_u32_e32 v38, -1, v33
	v_fma_f32 v39, -v38, v33, v32
	v_cmp_ge_f32_e64 s[38:39], 0, v39
	v_add_u32_e32 v39, 1, v33
	s_nop 0
	v_cndmask_b32_e64 v38, v33, v38, s[38:39]
	v_fma_f32 v33, -v39, v33, v32
	v_cmp_lt_f32_e64 s[38:39], 0, v33
	s_nop 1
	v_cndmask_b32_e64 v33, v38, v39, s[38:39]
	v_mul_f32_e32 v38, 0x37800000, v33
	v_cndmask_b32_e32 v33, v33, v38, vcc
	v_cmp_class_f32_e32 vcc, v32, v244
	s_nop 1
	v_cndmask_b32_e32 v32, v33, v32, vcc
	v_div_scale_f32 v33, s[4:5], v32, v32, 1.0
	v_rcp_f32_e32 v38, v33
	s_nop 0
	v_fma_f32 v39, -v33, v38, 1.0
	v_fmac_f32_e32 v38, v39, v38
	v_div_scale_f32 v39, vcc, 1.0, v32, 1.0
	v_mul_f32_e32 v40, v39, v38
	v_fma_f32 v41, -v33, v40, v39
	v_fmac_f32_e32 v40, v41, v38
	v_fma_f32 v33, -v33, v40, v39
	v_div_fmas_f32 v33, v33, v38, v40
	v_div_fixup_f32 v32, v33, v32, 1.0
	s_waitcnt vmcnt(9)
	v_lshlrev_b32_e32 v33, 16, v24
	v_mul_f32_e32 v38, 0xbfb8aa3b, v33
	v_exp_f32_e32 v38, v38
	v_and_b32_e32 v24, 0xffff0000, v24
	v_add_f32_e32 v38, 1.0, v38
	v_div_scale_f32 v39, s[4:5], v38, v38, v33
	v_rcp_f32_e32 v40, v39
	s_nop 0
	v_fma_f32 v41, -v39, v40, 1.0
	v_fmac_f32_e32 v40, v41, v40
	v_div_scale_f32 v41, vcc, v33, v38, v33
	v_mul_f32_e32 v42, v41, v40
	v_fma_f32 v43, -v39, v42, v41
	v_fmac_f32_e32 v42, v43, v40
	v_fma_f32 v39, -v39, v42, v41
	v_div_fmas_f32 v39, v39, v40, v42
	v_div_fixup_f32 v33, v39, v38, v33
	v_mul_f32_e32 v33, v36, v33
	v_mul_f32_e32 v36, 0xbfb8aa3b, v24
	v_exp_f32_e32 v36, v36
	v_mul_f32_e32 v33, v33, v32
	v_add_f32_e32 v36, 1.0, v36
	v_div_scale_f32 v38, s[4:5], v36, v36, v24
	v_rcp_f32_e32 v39, v38
	s_nop 0
	v_fma_f32 v40, -v38, v39, 1.0
	v_fmac_f32_e32 v39, v40, v39
	v_div_scale_f32 v40, vcc, v24, v36, v24
	v_mul_f32_e32 v41, v40, v39
	v_fma_f32 v42, -v38, v41, v40
	v_fmac_f32_e32 v41, v42, v39
	v_fma_f32 v38, -v38, v41, v40
	v_div_fmas_f32 v38, v38, v39, v41
	v_div_fixup_f32 v24, v38, v36, v24
	v_mul_f32_e32 v24, v28, v24
	v_mul_f32_e32 v24, v24, v32
	v_lshlrev_b32_e32 v28, 16, v25
	v_cvt_pk_bf16_f32 v24, v33, v24
	v_mul_f32_e32 v33, 0xbfb8aa3b, v28
	v_exp_f32_e32 v33, v33
	v_and_b32_e32 v25, 0xffff0000, v25
	v_add_f32_e32 v33, 1.0, v33
	v_div_scale_f32 v36, s[4:5], v33, v33, v28
	v_rcp_f32_e32 v38, v36
	s_nop 0
	v_fma_f32 v39, -v36, v38, 1.0
	v_fmac_f32_e32 v38, v39, v38
	v_div_scale_f32 v39, vcc, v28, v33, v28
	v_mul_f32_e32 v40, v39, v38
	v_fma_f32 v41, -v36, v40, v39
	v_fmac_f32_e32 v40, v41, v38
	v_fma_f32 v36, -v36, v40, v39
	v_div_fmas_f32 v36, v36, v38, v40
	v_div_fixup_f32 v28, v36, v33, v28
	v_mul_f32_e32 v33, 0xbfb8aa3b, v25
	v_exp_f32_e32 v33, v33
	v_mul_f32_e32 v28, v37, v28
	v_mul_f32_e32 v28, v28, v32
	v_add_f32_e32 v33, 1.0, v33
	v_div_scale_f32 v36, s[4:5], v33, v33, v25
	v_rcp_f32_e32 v37, v36
	s_nop 0
	v_fma_f32 v38, -v36, v37, 1.0
	v_fmac_f32_e32 v37, v38, v37
	v_div_scale_f32 v38, vcc, v25, v33, v25
	v_mul_f32_e32 v39, v38, v37
	v_fma_f32 v40, -v36, v39, v38
	v_fmac_f32_e32 v39, v40, v37
	v_fma_f32 v36, -v36, v39, v38
	v_div_fmas_f32 v36, v36, v37, v39
	v_div_fixup_f32 v25, v36, v33, v25
	v_mul_f32_e32 v25, v29, v25
	v_mul_f32_e32 v25, v25, v32
	v_cvt_pk_bf16_f32 v25, v28, v25
	v_lshlrev_b32_e32 v28, 16, v26
	v_mul_f32_e32 v29, 0xbfb8aa3b, v28
	v_exp_f32_e32 v29, v29
	v_and_b32_e32 v26, 0xffff0000, v26
	v_add_f32_e32 v29, 1.0, v29
	v_div_scale_f32 v33, s[4:5], v29, v29, v28
	v_rcp_f32_e32 v36, v33
	s_nop 0
	v_fma_f32 v37, -v33, v36, 1.0
	v_fmac_f32_e32 v36, v37, v36
	v_div_scale_f32 v37, vcc, v28, v29, v28
	v_mul_f32_e32 v38, v37, v36
	v_fma_f32 v39, -v33, v38, v37
	v_fmac_f32_e32 v38, v39, v36
	v_fma_f32 v33, -v33, v38, v37
	v_div_fmas_f32 v33, v33, v36, v38
	v_div_fixup_f32 v28, v33, v29, v28
	v_mul_f32_e32 v29, 0xbfb8aa3b, v26
	v_exp_f32_e32 v29, v29
	v_mul_f32_e32 v28, v31, v28
	v_mul_f32_e32 v28, v28, v32
	v_add_f32_e32 v29, 1.0, v29
	v_div_scale_f32 v31, s[4:5], v29, v29, v26
	v_rcp_f32_e32 v33, v31
	s_nop 0
	v_fma_f32 v36, -v31, v33, 1.0
	v_fmac_f32_e32 v33, v36, v33
	v_div_scale_f32 v36, vcc, v26, v29, v26
	v_mul_f32_e32 v37, v36, v33
	v_fma_f32 v38, -v31, v37, v36
	v_fmac_f32_e32 v37, v38, v33
	v_fma_f32 v31, -v31, v37, v36
	v_div_fmas_f32 v31, v31, v33, v37
	v_div_fixup_f32 v26, v31, v29, v26
	v_mul_f32_e32 v26, v35, v26
	v_mul_f32_e32 v26, v26, v32
	v_cvt_pk_bf16_f32 v26, v28, v26
	v_lshlrev_b32_e32 v28, 16, v27
	v_mul_f32_e32 v29, 0xbfb8aa3b, v28
	v_exp_f32_e32 v29, v29
	v_and_b32_e32 v27, 0xffff0000, v27
	v_add_f32_e32 v29, 1.0, v29
	v_div_scale_f32 v31, s[4:5], v29, v29, v28
	v_rcp_f32_e32 v33, v31
	s_nop 0
	v_fma_f32 v35, -v31, v33, 1.0
	v_fmac_f32_e32 v33, v35, v33
	v_div_scale_f32 v35, vcc, v28, v29, v28
	v_mul_f32_e32 v36, v35, v33
	v_fma_f32 v37, -v31, v36, v35
	v_fmac_f32_e32 v36, v37, v33
	v_fma_f32 v31, -v31, v36, v35
	v_div_fmas_f32 v31, v31, v33, v36
	v_div_fixup_f32 v28, v31, v29, v28
	v_mul_f32_e32 v29, 0xbfb8aa3b, v27
	v_exp_f32_e32 v29, v29
	v_mul_f32_e32 v28, v30, v28
	v_mul_f32_e32 v28, v28, v32
	v_add_f32_e32 v29, 1.0, v29
	v_div_scale_f32 v30, s[4:5], v29, v29, v27
	v_rcp_f32_e32 v31, v30
	s_nop 0
	v_fma_f32 v33, -v30, v31, 1.0
	v_fmac_f32_e32 v31, v33, v31
	v_div_scale_f32 v33, vcc, v27, v29, v27
	v_mul_f32_e32 v35, v33, v31
	v_fma_f32 v36, -v30, v35, v33
	v_fmac_f32_e32 v35, v36, v31
	v_fma_f32 v30, -v30, v35, v33
	v_div_fmas_f32 v30, v30, v31, v35
	v_div_fixup_f32 v27, v30, v29, v27
	v_mul_f32_e32 v27, v34, v27
	v_mul_f32_e32 v27, v27, v32
	v_cvt_pk_bf16_f32 v27, v28, v27
	v_lshlrev_b64 v[28:29], 13, v[84:85]
	v_lshl_add_u64 v[28:29], s[46:47], 0, v[28:29]
	v_lshl_add_u64 v[28:29], v[28:29], 0, v[86:87]
	v_lshl_add_u64 v[28:29], v[28:29], 0, v[74:75]
	global_store_dwordx4 v[28:29], v[24:27], off sc1
	s_waitcnt vmcnt(9)
	v_lshlrev_b32_e32 v29, 16, v18
	v_lshlrev_b32_e32 v28, 16, v19
	s_waitcnt vmcnt(8)
	v_lshlrev_b32_e32 v24, 16, v20
	v_lshlrev_b32_e32 v26, 16, v16
	v_lshlrev_b32_e32 v25, 16, v21
	v_lshlrev_b32_e32 v27, 16, v17
	v_and_b32_e32 v20, 0xffff0000, v20
	v_and_b32_e32 v16, 0xffff0000, v16
	v_and_b32_e32 v21, 0xffff0000, v21
	v_and_b32_e32 v17, 0xffff0000, v17
	v_pk_add_f32 v[24:25], v[26:27], v[24:25]
	v_lshlrev_b32_e32 v27, 16, v22
	v_lshlrev_b32_e32 v26, 16, v23
	v_pk_add_f32 v[16:17], v[16:17], v[20:21]
	v_pk_mul_f32 v[20:21], v[24:25], v[24:25]
	v_and_b32_e32 v31, 0xffff0000, v22
	v_and_b32_e32 v33, 0xffff0000, v18
	v_and_b32_e32 v30, 0xffff0000, v23
	v_and_b32_e32 v32, 0xffff0000, v19
	v_pk_add_f32 v[18:19], v[28:29], v[26:27]
	v_pk_fma_f32 v[20:21], v[16:17], v[16:17], v[20:21]
	v_pk_add_f32 v[22:23], v[32:33], v[30:31]
	v_pk_mul_f32 v[26:27], v[18:19], v[18:19]
	v_add_f32_e32 v20, v20, v21
	v_pk_fma_f32 v[26:27], v[22:23], v[22:23], v[26:27]
	s_nop 0
	v_add_f32_e32 v20, v27, v20
	v_add_f32_e32 v20, v26, v20
	s_nop 1
	v_add_f32_dpp v20, v20, v20 row_ror:8 row_mask:0xf bank_mask:0xf bound_ctrl:1
	s_nop 1
	v_add_f32_dpp v20, v20, v20 row_ror:4 row_mask:0xf bank_mask:0xf bound_ctrl:1
	s_nop 1
	v_add_f32_dpp v20, v20, v20 row_ror:2 row_mask:0xf bank_mask:0xf bound_ctrl:1
	s_nop 1
	v_add_f32_dpp v20, v20, v20 row_ror:1 row_mask:0xf bank_mask:0xf bound_ctrl:1
	s_nop 0
	v_readlane_b32 s1, v20, 16
	v_readlane_b32 s2, v20, 48
	v_readlane_b32 s4, v20, 0
	v_readlane_b32 s5, v20, 32
	v_mov_b32_e32 v20, s1
	v_mov_b32_e32 v21, s2
	v_pk_add_f32 v[20:21], s[4:5], v[20:21]
	s_nop 0
	v_add_f32_e32 v20, v20, v21
	v_fmamk_f32 v20, v20, 0x3b000000, v173
	v_cmp_gt_f32_e32 vcc, s19, v20
	v_mul_f32_e32 v21, 0x4f800000, v20
	s_nop 0
	v_cndmask_b32_e32 v20, v20, v21, vcc
	v_sqrt_f32_e32 v21, v20
	s_nop 0
	v_add_u32_e32 v26, -1, v21
	v_fma_f32 v27, -v26, v21, v20
	v_cmp_ge_f32_e64 s[38:39], 0, v27
	v_add_u32_e32 v27, 1, v21
	s_nop 0
	v_cndmask_b32_e64 v26, v21, v26, s[38:39]
	v_fma_f32 v21, -v27, v21, v20
	v_cmp_lt_f32_e64 s[38:39], 0, v21
	s_nop 1
	v_cndmask_b32_e64 v21, v26, v27, s[38:39]
	v_mul_f32_e32 v26, 0x37800000, v21
	v_cndmask_b32_e32 v21, v21, v26, vcc
	v_cmp_class_f32_e32 vcc, v20, v244
	s_nop 1
	v_cndmask_b32_e32 v20, v21, v20, vcc
	v_div_scale_f32 v21, s[4:5], v20, v20, 1.0
	v_rcp_f32_e32 v26, v21
	s_nop 0
	v_fma_f32 v27, -v21, v26, 1.0
	v_fmac_f32_e32 v26, v27, v26
	v_div_scale_f32 v27, vcc, 1.0, v20, 1.0
	v_mul_f32_e32 v28, v27, v26
	v_fma_f32 v29, -v21, v28, v27
	v_fmac_f32_e32 v28, v29, v26
	v_fma_f32 v21, -v21, v28, v27
	v_div_fmas_f32 v21, v21, v26, v28
	v_div_fixup_f32 v20, v21, v20, 1.0
	s_waitcnt vmcnt(7)
	v_lshlrev_b32_e32 v21, 16, v12
	v_mul_f32_e32 v26, 0xbfb8aa3b, v21
	v_exp_f32_e32 v26, v26
	v_and_b32_e32 v12, 0xffff0000, v12
	v_add_f32_e32 v26, 1.0, v26
	v_div_scale_f32 v27, s[4:5], v26, v26, v21
	v_rcp_f32_e32 v28, v27
	s_nop 0
	v_fma_f32 v29, -v27, v28, 1.0
	v_fmac_f32_e32 v28, v29, v28
	v_div_scale_f32 v29, vcc, v21, v26, v21
	v_mul_f32_e32 v30, v29, v28
	v_fma_f32 v31, -v27, v30, v29
	v_fmac_f32_e32 v30, v31, v28
	v_fma_f32 v27, -v27, v30, v29
	v_div_fmas_f32 v27, v27, v28, v30
	v_div_fixup_f32 v21, v27, v26, v21
	v_mul_f32_e32 v21, v24, v21
	v_mul_f32_e32 v24, 0xbfb8aa3b, v12
	v_exp_f32_e32 v24, v24
	v_mul_f32_e32 v21, v21, v20
	v_add_f32_e32 v24, 1.0, v24
	v_div_scale_f32 v26, s[4:5], v24, v24, v12
	v_rcp_f32_e32 v27, v26
	s_nop 0
	v_fma_f32 v28, -v26, v27, 1.0
	v_fmac_f32_e32 v27, v28, v27
	v_div_scale_f32 v28, vcc, v12, v24, v12
	v_mul_f32_e32 v29, v28, v27
	v_fma_f32 v30, -v26, v29, v28
	v_fmac_f32_e32 v29, v30, v27
	v_fma_f32 v26, -v26, v29, v28
	v_div_fmas_f32 v26, v26, v27, v29
	v_div_fixup_f32 v12, v26, v24, v12
	v_mul_f32_e32 v12, v16, v12
	v_mul_f32_e32 v12, v12, v20
	v_lshlrev_b32_e32 v16, 16, v13
	v_cvt_pk_bf16_f32 v12, v21, v12
	v_mul_f32_e32 v21, 0xbfb8aa3b, v16
	v_exp_f32_e32 v21, v21
	v_and_b32_e32 v13, 0xffff0000, v13
	v_add_f32_e32 v21, 1.0, v21
	v_div_scale_f32 v24, s[4:5], v21, v21, v16
	v_rcp_f32_e32 v26, v24
	s_nop 0
	v_fma_f32 v27, -v24, v26, 1.0
	v_fmac_f32_e32 v26, v27, v26
	v_div_scale_f32 v27, vcc, v16, v21, v16
	v_mul_f32_e32 v28, v27, v26
	v_fma_f32 v29, -v24, v28, v27
	v_fmac_f32_e32 v28, v29, v26
	v_fma_f32 v24, -v24, v28, v27
	v_div_fmas_f32 v24, v24, v26, v28
	v_div_fixup_f32 v16, v24, v21, v16
	v_mul_f32_e32 v21, 0xbfb8aa3b, v13
	v_exp_f32_e32 v21, v21
	v_mul_f32_e32 v16, v25, v16
	v_mul_f32_e32 v16, v16, v20
	v_add_f32_e32 v21, 1.0, v21
	v_div_scale_f32 v24, s[4:5], v21, v21, v13
	v_rcp_f32_e32 v25, v24
	s_nop 0
	v_fma_f32 v26, -v24, v25, 1.0
	v_fmac_f32_e32 v25, v26, v25
	v_div_scale_f32 v26, vcc, v13, v21, v13
	v_mul_f32_e32 v27, v26, v25
	v_fma_f32 v28, -v24, v27, v26
	v_fmac_f32_e32 v27, v28, v25
	v_fma_f32 v24, -v24, v27, v26
	v_div_fmas_f32 v24, v24, v25, v27
	v_div_fixup_f32 v13, v24, v21, v13
	v_mul_f32_e32 v13, v17, v13
	v_mul_f32_e32 v13, v13, v20
	v_cvt_pk_bf16_f32 v13, v16, v13
	v_lshlrev_b32_e32 v16, 16, v14
	v_mul_f32_e32 v17, 0xbfb8aa3b, v16
	v_exp_f32_e32 v17, v17
	v_and_b32_e32 v14, 0xffff0000, v14
	v_add_f32_e32 v17, 1.0, v17
	v_div_scale_f32 v21, s[4:5], v17, v17, v16
	v_rcp_f32_e32 v24, v21
	s_nop 0
	v_fma_f32 v25, -v21, v24, 1.0
	v_fmac_f32_e32 v24, v25, v24
	v_div_scale_f32 v25, vcc, v16, v17, v16
	v_mul_f32_e32 v26, v25, v24
	v_fma_f32 v27, -v21, v26, v25
	v_fmac_f32_e32 v26, v27, v24
	v_fma_f32 v21, -v21, v26, v25
	v_div_fmas_f32 v21, v21, v24, v26
	v_div_fixup_f32 v16, v21, v17, v16
	v_mul_f32_e32 v17, 0xbfb8aa3b, v14
	v_exp_f32_e32 v17, v17
	v_mul_f32_e32 v16, v19, v16
	v_mul_f32_e32 v16, v16, v20
	v_add_f32_e32 v17, 1.0, v17
	v_div_scale_f32 v19, s[4:5], v17, v17, v14
	v_rcp_f32_e32 v21, v19
	s_nop 0
	v_fma_f32 v24, -v19, v21, 1.0
	v_fmac_f32_e32 v21, v24, v21
	v_div_scale_f32 v24, vcc, v14, v17, v14
	v_mul_f32_e32 v25, v24, v21
	v_fma_f32 v26, -v19, v25, v24
	v_fmac_f32_e32 v25, v26, v21
	v_fma_f32 v19, -v19, v25, v24
	v_div_fmas_f32 v19, v19, v21, v25
	v_div_fixup_f32 v14, v19, v17, v14
	v_mul_f32_e32 v14, v23, v14
	v_mul_f32_e32 v14, v14, v20
	v_cvt_pk_bf16_f32 v14, v16, v14
	v_lshlrev_b32_e32 v16, 16, v15
	v_mul_f32_e32 v17, 0xbfb8aa3b, v16
	v_exp_f32_e32 v17, v17
	v_and_b32_e32 v15, 0xffff0000, v15
	v_add_f32_e32 v17, 1.0, v17
	v_div_scale_f32 v19, s[4:5], v17, v17, v16
	v_rcp_f32_e32 v21, v19
	s_nop 0
	v_fma_f32 v23, -v19, v21, 1.0
	v_fmac_f32_e32 v21, v23, v21
	v_div_scale_f32 v23, vcc, v16, v17, v16
	v_mul_f32_e32 v24, v23, v21
	v_fma_f32 v25, -v19, v24, v23
	v_fmac_f32_e32 v24, v25, v21
	v_fma_f32 v19, -v19, v24, v23
	v_div_fmas_f32 v19, v19, v21, v24
	v_div_fixup_f32 v16, v19, v17, v16
	v_mul_f32_e32 v17, 0xbfb8aa3b, v15
	v_exp_f32_e32 v17, v17
	v_mul_f32_e32 v16, v18, v16
	v_mul_f32_e32 v16, v16, v20
	v_add_f32_e32 v17, 1.0, v17
	v_div_scale_f32 v18, s[4:5], v17, v17, v15
	v_rcp_f32_e32 v19, v18
	s_nop 0
	v_fma_f32 v21, -v18, v19, 1.0
	v_fmac_f32_e32 v19, v21, v19
	v_div_scale_f32 v21, vcc, v15, v17, v15
	v_mul_f32_e32 v23, v21, v19
	v_fma_f32 v24, -v18, v23, v21
	v_fmac_f32_e32 v23, v24, v19
	v_fma_f32 v18, -v18, v23, v21
	v_div_fmas_f32 v18, v18, v19, v23
	v_div_fixup_f32 v15, v18, v17, v15
	v_mul_f32_e32 v15, v22, v15
	v_mul_f32_e32 v15, v15, v20
	v_cvt_pk_bf16_f32 v15, v16, v15
	v_lshlrev_b64 v[16:17], 13, v[80:81]
	v_lshl_add_u64 v[16:17], s[46:47], 0, v[16:17]
	v_lshl_add_u64 v[16:17], v[16:17], 0, v[82:83]
	v_lshl_add_u64 v[16:17], v[16:17], 0, v[74:75]
	global_store_dwordx4 v[16:17], v[12:15], off sc1
	s_waitcnt vmcnt(7)
	v_lshlrev_b32_e32 v17, 16, v6
	v_lshlrev_b32_e32 v16, 16, v7
	s_waitcnt vmcnt(6)
	v_lshlrev_b32_e32 v12, 16, v8
	v_lshlrev_b32_e32 v14, 16, v4
	v_lshlrev_b32_e32 v13, 16, v9
	v_lshlrev_b32_e32 v15, 16, v5
	v_and_b32_e32 v8, 0xffff0000, v8
	v_and_b32_e32 v4, 0xffff0000, v4
	v_and_b32_e32 v9, 0xffff0000, v9
	v_and_b32_e32 v5, 0xffff0000, v5
	v_pk_add_f32 v[12:13], v[14:15], v[12:13]
	v_lshlrev_b32_e32 v15, 16, v10
	v_lshlrev_b32_e32 v14, 16, v11
	v_pk_add_f32 v[4:5], v[4:5], v[8:9]
	v_pk_mul_f32 v[8:9], v[12:13], v[12:13]
	v_and_b32_e32 v19, 0xffff0000, v10
	v_and_b32_e32 v21, 0xffff0000, v6
	v_and_b32_e32 v18, 0xffff0000, v11
	v_and_b32_e32 v20, 0xffff0000, v7
	v_pk_add_f32 v[6:7], v[16:17], v[14:15]
	v_pk_fma_f32 v[8:9], v[4:5], v[4:5], v[8:9]
	v_pk_add_f32 v[10:11], v[20:21], v[18:19]
	v_pk_mul_f32 v[14:15], v[6:7], v[6:7]
	v_add_f32_e32 v8, v8, v9
	v_pk_fma_f32 v[14:15], v[10:11], v[10:11], v[14:15]
	s_nop 0
	v_add_f32_e32 v8, v15, v8
	v_add_f32_e32 v8, v14, v8
	s_nop 1
	v_add_f32_dpp v8, v8, v8 row_ror:8 row_mask:0xf bank_mask:0xf bound_ctrl:1
	s_nop 1
	v_add_f32_dpp v8, v8, v8 row_ror:4 row_mask:0xf bank_mask:0xf bound_ctrl:1
	s_nop 1
	v_add_f32_dpp v8, v8, v8 row_ror:2 row_mask:0xf bank_mask:0xf bound_ctrl:1
	s_nop 1
	v_add_f32_dpp v8, v8, v8 row_ror:1 row_mask:0xf bank_mask:0xf bound_ctrl:1
	s_nop 0
	v_readlane_b32 s1, v8, 16
	v_readlane_b32 s2, v8, 48
	v_readlane_b32 s4, v8, 0
	v_readlane_b32 s5, v8, 32
	v_mov_b32_e32 v8, s1
	v_mov_b32_e32 v9, s2
	v_pk_add_f32 v[8:9], s[4:5], v[8:9]
	s_mul_i32 s2, s94, 48
	v_add_f32_e32 v8, v8, v9
	v_fmamk_f32 v8, v8, 0x3b000000, v173
	v_cmp_gt_f32_e32 vcc, s19, v8
	v_mul_f32_e32 v9, 0x4f800000, v8
	s_mul_i32 s1, s94, 0x6000
	v_cndmask_b32_e32 v8, v8, v9, vcc
	v_sqrt_f32_e32 v9, v8
	v_add_u32_e32 v73, s2, v73
	v_add_u32_e32 v94, s1, v94
	s_mov_b32 s1, 0x11fff
	v_add_u32_e32 v14, -1, v9
	v_fma_f32 v15, -v14, v9, v8
	v_cmp_ge_f32_e64 s[38:39], 0, v15
	v_add_u32_e32 v15, 1, v9
	s_nop 0
	v_cndmask_b32_e64 v14, v9, v14, s[38:39]
	v_fma_f32 v9, -v15, v9, v8
	v_cmp_lt_f32_e64 s[38:39], 0, v9
	s_nop 1
	v_cndmask_b32_e64 v9, v14, v15, s[38:39]
	v_mul_f32_e32 v14, 0x37800000, v9
	v_cndmask_b32_e32 v9, v9, v14, vcc
	v_cmp_class_f32_e32 vcc, v8, v244
	s_nop 1
	v_cndmask_b32_e32 v8, v9, v8, vcc
	v_div_scale_f32 v9, s[4:5], v8, v8, 1.0
	v_rcp_f32_e32 v14, v9
	s_nop 0
	v_fma_f32 v15, -v9, v14, 1.0
	v_fmac_f32_e32 v14, v15, v14
	v_div_scale_f32 v15, vcc, 1.0, v8, 1.0
	v_mul_f32_e32 v16, v15, v14
	v_fma_f32 v17, -v9, v16, v15
	v_fmac_f32_e32 v16, v17, v14
	v_fma_f32 v9, -v9, v16, v15
	v_div_fmas_f32 v9, v9, v14, v16
	v_div_fixup_f32 v8, v9, v8, 1.0
	s_waitcnt vmcnt(5)
	v_lshlrev_b32_e32 v9, 16, v0
	v_mul_f32_e32 v14, 0xbfb8aa3b, v9
	v_exp_f32_e32 v14, v14
	v_and_b32_e32 v0, 0xffff0000, v0
	v_add_f32_e32 v14, 1.0, v14
	v_div_scale_f32 v15, s[4:5], v14, v14, v9
	v_rcp_f32_e32 v16, v15
	s_nop 0
	v_fma_f32 v17, -v15, v16, 1.0
	v_fmac_f32_e32 v16, v17, v16
	v_div_scale_f32 v17, vcc, v9, v14, v9
	v_mul_f32_e32 v18, v17, v16
	v_fma_f32 v19, -v15, v18, v17
	v_fmac_f32_e32 v18, v19, v16
	v_fma_f32 v15, -v15, v18, v17
	v_div_fmas_f32 v15, v15, v16, v18
	v_div_fixup_f32 v9, v15, v14, v9
	v_mul_f32_e32 v9, v12, v9
	v_mul_f32_e32 v12, 0xbfb8aa3b, v0
	v_exp_f32_e32 v12, v12
	v_mul_f32_e32 v9, v9, v8
	v_add_f32_e32 v12, 1.0, v12
	v_div_scale_f32 v14, s[4:5], v12, v12, v0
	v_rcp_f32_e32 v15, v14
	s_nop 0
	v_fma_f32 v16, -v14, v15, 1.0
	v_fmac_f32_e32 v15, v16, v15
	v_div_scale_f32 v16, vcc, v0, v12, v0
	v_mul_f32_e32 v17, v16, v15
	v_fma_f32 v18, -v14, v17, v16
	v_fmac_f32_e32 v17, v18, v15
	v_fma_f32 v14, -v14, v17, v16
	v_div_fmas_f32 v14, v14, v15, v17
	v_div_fixup_f32 v0, v14, v12, v0
	v_mul_f32_e32 v0, v4, v0
	v_mul_f32_e32 v0, v0, v8
	v_lshlrev_b32_e32 v4, 16, v1
	v_cvt_pk_bf16_f32 v0, v9, v0
	v_mul_f32_e32 v9, 0xbfb8aa3b, v4
	v_exp_f32_e32 v9, v9
	v_and_b32_e32 v1, 0xffff0000, v1
	v_add_f32_e32 v9, 1.0, v9
	v_div_scale_f32 v12, s[4:5], v9, v9, v4
	v_rcp_f32_e32 v14, v12
	s_nop 0
	v_fma_f32 v15, -v12, v14, 1.0
	v_fmac_f32_e32 v14, v15, v14
	v_div_scale_f32 v15, vcc, v4, v9, v4
	v_mul_f32_e32 v16, v15, v14
	v_fma_f32 v17, -v12, v16, v15
	v_fmac_f32_e32 v16, v17, v14
	v_fma_f32 v12, -v12, v16, v15
	v_div_fmas_f32 v12, v12, v14, v16
	v_div_fixup_f32 v4, v12, v9, v4
	v_mul_f32_e32 v9, 0xbfb8aa3b, v1
	v_exp_f32_e32 v9, v9
	v_mul_f32_e32 v4, v13, v4
	v_mul_f32_e32 v4, v4, v8
	v_add_f32_e32 v9, 1.0, v9
	v_div_scale_f32 v12, s[4:5], v9, v9, v1
	v_rcp_f32_e32 v13, v12
	s_nop 0
	v_fma_f32 v14, -v12, v13, 1.0
	v_fmac_f32_e32 v13, v14, v13
	v_div_scale_f32 v14, vcc, v1, v9, v1
	v_mul_f32_e32 v15, v14, v13
	v_fma_f32 v16, -v12, v15, v14
	v_fmac_f32_e32 v15, v16, v13
	v_fma_f32 v12, -v12, v15, v14
	v_div_fmas_f32 v12, v12, v13, v15
	v_div_fixup_f32 v1, v12, v9, v1
	v_mul_f32_e32 v1, v5, v1
	v_mul_f32_e32 v1, v1, v8
	v_cvt_pk_bf16_f32 v1, v4, v1
	v_lshlrev_b32_e32 v4, 16, v2
	v_mul_f32_e32 v5, 0xbfb8aa3b, v4
	v_exp_f32_e32 v5, v5
	v_and_b32_e32 v2, 0xffff0000, v2
	v_add_f32_e32 v5, 1.0, v5
	v_div_scale_f32 v9, s[4:5], v5, v5, v4
	v_rcp_f32_e32 v12, v9
	s_nop 0
	v_fma_f32 v13, -v9, v12, 1.0
	v_fmac_f32_e32 v12, v13, v12
	v_div_scale_f32 v13, vcc, v4, v5, v4
	v_mul_f32_e32 v14, v13, v12
	v_fma_f32 v15, -v9, v14, v13
	v_fmac_f32_e32 v14, v15, v12
	v_fma_f32 v9, -v9, v14, v13
	v_div_fmas_f32 v9, v9, v12, v14
	v_div_fixup_f32 v4, v9, v5, v4
	v_mul_f32_e32 v5, 0xbfb8aa3b, v2
	v_exp_f32_e32 v5, v5
	v_mul_f32_e32 v4, v7, v4
	v_mul_f32_e32 v4, v4, v8
	v_add_f32_e32 v5, 1.0, v5
	v_div_scale_f32 v7, s[4:5], v5, v5, v2
	v_rcp_f32_e32 v9, v7
	s_nop 0
	v_fma_f32 v12, -v7, v9, 1.0
	v_fmac_f32_e32 v9, v12, v9
	v_div_scale_f32 v12, vcc, v2, v5, v2
	v_mul_f32_e32 v13, v12, v9
	v_fma_f32 v14, -v7, v13, v12
	v_fmac_f32_e32 v13, v14, v9
	v_fma_f32 v7, -v7, v13, v12
	v_div_fmas_f32 v7, v7, v9, v13
	v_div_fixup_f32 v2, v7, v5, v2
	v_mul_f32_e32 v2, v11, v2
	v_mul_f32_e32 v2, v2, v8
	v_cvt_pk_bf16_f32 v2, v4, v2
	v_lshlrev_b32_e32 v4, 16, v3
	v_mul_f32_e32 v5, 0xbfb8aa3b, v4
	v_exp_f32_e32 v5, v5
	v_and_b32_e32 v3, 0xffff0000, v3
	v_add_f32_e32 v5, 1.0, v5
	v_div_scale_f32 v7, s[4:5], v5, v5, v4
	v_rcp_f32_e32 v9, v7
	s_nop 0
	v_fma_f32 v11, -v7, v9, 1.0
	v_fmac_f32_e32 v9, v11, v9
	v_div_scale_f32 v11, vcc, v4, v5, v4
	v_mul_f32_e32 v12, v11, v9
	v_fma_f32 v13, -v7, v12, v11
	v_fmac_f32_e32 v12, v13, v9
	v_fma_f32 v7, -v7, v12, v11
	v_div_fmas_f32 v7, v7, v9, v12
	v_div_fixup_f32 v4, v7, v5, v4
	v_mul_f32_e32 v5, 0xbfb8aa3b, v3
	v_exp_f32_e32 v5, v5
	v_mul_f32_e32 v4, v6, v4
	v_mul_f32_e32 v4, v4, v8
	v_add_f32_e32 v5, 1.0, v5
	v_div_scale_f32 v6, s[4:5], v5, v5, v3
	v_rcp_f32_e32 v7, v6
	s_nop 0
	v_fma_f32 v9, -v6, v7, 1.0
	v_fmac_f32_e32 v7, v9, v7
	v_div_scale_f32 v9, vcc, v3, v5, v3
	v_mul_f32_e32 v11, v9, v7
	v_fma_f32 v12, -v6, v11, v9
	v_fmac_f32_e32 v11, v12, v7
	v_fma_f32 v6, -v6, v11, v9
	v_div_fmas_f32 v6, v6, v7, v11
	v_div_fixup_f32 v3, v6, v5, v3
	v_mul_f32_e32 v3, v10, v3
	v_mul_f32_e32 v3, v3, v8
	v_cvt_pk_bf16_f32 v3, v4, v3
	v_lshlrev_b64 v[4:5], 13, v[78:79]
	v_lshl_add_u64 v[4:5], s[46:47], 0, v[4:5]
	v_lshl_add_u64 v[4:5], v[4:5], 0, v[76:77]
	v_cmp_lt_i32_e32 vcc, s1, v73
	v_lshl_add_u64 v[4:5], v[4:5], 0, v[74:75]
	s_or_b64 s[50:51], vcc, s[50:51]
	global_store_dwordx4 v[4:5], v[0:3], off sc1
	s_andn2_b64 exec, exec, s[50:51]
	s_cbranch_execnz .LBB0_405
